# windowed attention: LUT bias reads batched/prefetched before the bias adds
# speedup vs baseline: 1.0133x; 1.0046x over previous
; #define LAS __attribute__((address_space(3)))
; __device__ __forceinline__ void attn_win(LAS unsigned char* lds, const bf16_t* __restrict__ PROJ, const bf16_t* __restrict__ VT, bf16_t* __restrict__ AO, ...
;     ...
;         const int k0 = t * 64;
;         if ((k0 + 63 >= qw - 128) && (k0 <= qw + 31 + 128)) {
;             const LAS unsigned char* kb = lds + OFF_K + cur * TB + r32 * KP + hi * 16;
;             f32x16 sA = {}, sB = {};
; #pragma unroll
;             for (int ds = 0; ds < 4; ++ds) {
;                 const bf16x8 ka = *(const LAS bf16x8*)(kb + ds * 32);
;                 const bf16x8 kb2 = *(const LAS bf16x8*)(kb + 32 * KP + ds * 32);
;                 sA = __builtin_amdgcn_mfma_f32_32x32x16_bf16(ka, qf[ds], sA, 0, 0, 0);
;                 sB = __builtin_amdgcn_mfma_f32_32x32x16_bf16(kb2, qf[ds], sB, 0, 0, 0);
;             }
;             { const LAS float* lp = lut + (k0 - (qw + r32) + 224 + 4 * hi);
; #pragma unroll
;               for (int r = 0; r < 16; ++r) { sA[r] += lp[(r & 3) + 8 * (r >> 2)]; sB[r] += lp[32 + (r & 3) + 8 * (r >> 2)]; } }
;             float mx0 = fmaxf(sA[0], sB[0]), mx1 = fmaxf(sA[1], sB[1]), mx2 = fmaxf(sA[2], sB[2]), mx3 = fmaxf(sA[3], sB[3]);
; #pragma unroll
;             for (int r = 4; r < 16; r += 4) { mx0 = fmaxf(mx0, fmaxf(sA[r], sB[r])); mx1 = fmaxf(mx1, fmaxf(sA[r + 1], sB[r + 1])); mx2 = fmaxf(mx2, fmaxf(sA[r + 2], sB[r + 2])); mx3 = fmaxf(mx3, fmaxf(sA[r + 3], sB[r + 3])); }
;             float mx = fmaxf(fmaxf(mx0, mx1), fmaxf(mx2, mx3));
;             mx = fmaxf(mx, __shfl_xor(mx, 32));
.LBB0_268:
	s_add_i32 s30, s10, 63
	s_cmp_lt_i32 s30, s11
	s_cselect_b64 s[30:31], -1, 0
	s_cmp_gt_u32 s10, s12
	s_cselect_b64 s[64:65], -1, 0
	s_or_b64 s[30:31], s[30:31], s[64:65]
	s_and_b64 vcc, exec, s[30:31]
	s_cbranch_vccnz .LBB0_264
	s_mulk_i32 s14, 0x2400
	v_add_u32_e32 v97, s14, v95
	ds_read_b128 v[48:51], v97 offset:4608
	s_waitcnt lgkmcnt(3)
	ds_read_b128 v[32:35], v97
	ds_read_b128 v[100:103], v97 offset:32
	ds_read_b128 v[104:107], v97 offset:4640
	s_waitcnt lgkmcnt(3)
	v_mfma_f32_32x32x16_bf16 v[48:63], v[48:51], v[64:67], 0
	s_waitcnt lgkmcnt(2)
	v_mfma_f32_32x32x16_bf16 v[32:47], v[32:35], v[64:67], 0
	s_waitcnt lgkmcnt(1)
	v_mfma_f32_32x32x16_bf16 v[32:47], v[100:103], v[68:71], v[32:47]
	s_waitcnt lgkmcnt(0)
	v_mfma_f32_32x32x16_bf16 v[48:63], v[104:107], v[68:71], v[48:63]
	ds_read_b128 v[100:103], v97 offset:64
	ds_read_b128 v[104:107], v97 offset:4672
	s_waitcnt vmcnt(1) lgkmcnt(1)
	v_mfma_f32_32x32x16_bf16 v[32:47], v[100:103], v[72:75], v[32:47]
	s_waitcnt lgkmcnt(0)
	v_mfma_f32_32x32x16_bf16 v[48:63], v[104:107], v[72:75], v[48:63]
	ds_read_b128 v[100:103], v97 offset:96
	ds_read_b128 v[104:107], v97 offset:4704
	s_waitcnt vmcnt(0) lgkmcnt(1)
	v_mfma_f32_32x32x16_bf16 v[32:47], v[100:103], v[80:83], v[32:47]
	ds_read2_b32 v[206:207], v96 offset1:1
	ds_read2_b32 v[208:209], v96 offset0:32 offset1:33
	ds_read2_b32 v[210:211], v96 offset0:2 offset1:3
	ds_read2_b32 v[212:213], v96 offset0:34 offset1:35
	ds_read2_b32 v[214:215], v96 offset0:8 offset1:9
	ds_read2_b32 v[216:217], v96 offset0:40 offset1:41
	ds_read2_b32 v[218:219], v96 offset0:10 offset1:11
	ds_read2_b32 v[220:221], v96 offset0:42 offset1:43
	ds_read2_b32 v[222:223], v96 offset0:16 offset1:17
	ds_read2_b32 v[224:225], v96 offset0:48 offset1:49
	ds_read2_b32 v[226:227], v96 offset0:18 offset1:19
	ds_read2_b32 v[228:229], v96 offset0:50 offset1:51
	ds_read2_b32 v[230:231], v96 offset0:24 offset1:25
	ds_read2_b32 v[232:233], v96 offset0:56 offset1:57
	s_waitcnt lgkmcnt(14)
	v_mfma_f32_32x32x16_bf16 v[48:63], v[104:107], v[80:83], v[48:63]
	ds_read2_b32 v[234:235], v96 offset0:26 offset1:27
	ds_read2_b32 v[236:237], v96 offset0:58 offset1:59
	s_waitcnt lgkmcnt(0)
	s_nop 6
	v_add_f32_e32 v99, v32, v206
	v_add_f32_e32 v101, v33, v207
	v_add_f32_e32 v100, v48, v208
	v_add_f32_e32 v102, v49, v209
	v_add_f32_e32 v103, v34, v210
	v_add_f32_e32 v48, v50, v212
	v_add_f32_e32 v50, v35, v211
	v_add_f32_e32 v49, v51, v213
	v_add_f32_e32 v51, v36, v214
	v_add_f32_e32 v52, v52, v216
	v_add_f32_e32 v104, v37, v215
	v_add_f32_e32 v53, v53, v217
	v_add_f32_e32 v105, v38, v218
	v_add_f32_e32 v54, v54, v220
	v_add_f32_e32 v106, v39, v219
	v_add_f32_e32 v55, v55, v221
	v_max_f32_e32 v36, v106, v55
	v_max3_f32 v36, v50, v49, v36
	v_add_f32_e32 v107, v40, v222
	v_add_f32_e32 v108, v56, v224
	v_add_f32_e32 v109, v41, v223
	v_add_f32_e32 v57, v57, v225
	v_max_f32_e32 v37, v107, v108
	v_max_f32_e32 v38, v109, v57
	v_add_f32_e32 v110, v42, v226
	v_add_f32_e32 v111, v58, v228
	v_add_f32_e32 v112, v43, v227
	v_add_f32_e32 v113, v59, v229
	v_max_f32_e32 v39, v110, v111
	v_add_f32_e32 v44, v44, v230
	v_add_f32_e32 v114, v60, v232
	v_add_f32_e32 v115, v45, v231
	v_add_f32_e32 v116, v61, v233
	v_add_f32_e32 v117, v46, v234
	v_add_f32_e32 v119, v47, v235
	v_add_f32_e32 v120, v63, v237
	v_max_f32_e32 v32, v103, v48
	v_max_f32_e32 v33, v51, v52
	v_max_f32_e32 v35, v105, v54
	v_add_f32_e32 v118, v62, v236
	v_max3_f32 v33, v99, v100, v33
	v_max_f32_e32 v34, v104, v53
	v_max3_f32 v32, v32, v35, v39
	v_max_f32_e32 v39, v44, v114
	v_max3_f32 v34, v101, v102, v34
	v_max3_f32 v33, v33, v37, v39
	v_max_f32_e32 v37, v115, v116
	v_max_f32_e32 v35, v112, v113
	v_max3_f32 v34, v34, v38, v37
	v_max_f32_e32 v38, v119, v120
	v_max_f32_e32 v37, v117, v118
	v_max3_f32 v35, v36, v35, v38
	v_max3_f32 v32, v32, v37, v35
	v_max3_f32 v32, v33, v34, v32
	ds_bpermute_b32 v33, v166, v32
	s_waitcnt lgkmcnt(0)
; #define LAS __attribute__((address_space(3)))
; __device__ __forceinline__ unsigned cvtpk(float lo, float hi) { f32x2_t v = {lo, hi}; bf16x2_t b = __builtin_convertvector(v, bf16x2_t); return __builtin_bit_cast(unsigned, b); }
; __device__ __forceinline__ void attn_win(LAS unsigned char* lds, const bf16_t* __restrict__ PROJ, const bf16_t* __restrict__ VT, bf16_t* __restrict__ AO, ...
;     ...
;             const float mn = fmaxf(m, mx);
;             const float alpha = __builtin_amdgcn_exp2f(m - mn);
;             m = mn;
;             float ps0 = 0.f, ps1 = 0.f, ps2 = 0.f, ps3 = 0.f;
; #pragma unroll
;             for (int r = 0; r < 16; r += 4) {
; #pragma unroll
;                 for (int q = 0; q < 4; ++q) { sA[r + q] = __builtin_amdgcn_exp2f(sA[r + q] - mn); sB[r + q] = __builtin_amdgcn_exp2f(sB[r + q] - mn); }
;                 ps0 += sA[r] + sB[r]; ps1 += sA[r + 1] + sB[r + 1]; ps2 += sA[r + 2] + sB[r + 2]; ps3 += sA[r + 3] + sB[r + 3]; }
;             l = l * alpha + ((ps0 + ps1) + (ps2 + ps3));
; #pragma unroll
;             for (int r = 0; r < 16; ++r) { o0[r] *= alpha; o1[r] *= alpha; }
;             bf16x8 pk[4];
;             { u32x4 w;
;               w.x = cvtpk(sA[0], sA[1]); w.y = cvtpk(sA[2], sA[3]); w.z = cvtpk(sA[4], sA[5]); w.w = cvtpk(sA[6], sA[7]); pk[0] = __builtin_bit_cast(bf16x8, w);
;               w.x = cvtpk(sA[8], sA[9]); w.y = cvtpk(sA[10], sA[11]); w.z = cvtpk(sA[12], sA[13]); w.w = cvtpk(sA[14], sA[15]); pk[1] = __builtin_bit_cast(bf16x8, w);
;               w.x = cvtpk(sB[0], sB[1]); w.y = cvtpk(sB[2], sB[3]); w.z = cvtpk(sB[4], sB[5]); w.w = cvtpk(sB[6], sB[7]); pk[2] = __builtin_bit_cast(bf16x8, w);
;               w.x = cvtpk(sB[8], sB[9]); w.y = cvtpk(sB[10], sB[11]); w.z = cvtpk(sB[12], sB[13]); w.w = cvtpk(sB[14], sB[15]); pk[3] = __builtin_bit_cast(bf16x8, w); }
;             const LAS unsigned char* vb = lds + OFF_V + cur * TB + r32 * KP + hi * 16;
; #pragma unroll
;             for (int s = 0; s < 4; ++s) {
;                 const bf16x8 va = *(const LAS bf16x8*)(vb + s * 32);
;                 const bf16x8 vb2 = *(const LAS bf16x8*)(vb + 32 * KP + s * 32);
;                 o0 = __builtin_amdgcn_mfma_f32_32x32x16_bf16(va, pk[s], o0, 0, 0, 0);
;                 o1 = __builtin_amdgcn_mfma_f32_32x32x16_bf16(vb2, pk[s], o1, 0, 0, 0);
;             }
	v_max3_f32 v45, v98, v32, v33
	v_sub_f32_e32 v33, v101, v45
	v_sub_f32_e32 v35, v50, v45
	v_sub_f32_e32 v50, v107, v45
	v_exp_f32_e32 v38, v33
	v_sub_f32_e32 v33, v102, v45
	v_sub_f32_e32 v41, v52, v45
	v_exp_f32_e32 v56, v50
	v_sub_f32_e32 v50, v108, v45
	v_sub_f32_e32 v32, v99, v45
	v_exp_f32_e32 v34, v33
	v_sub_f32_e32 v33, v103, v45
	v_exp_f32_e32 v46, v41
	v_sub_f32_e32 v41, v104, v45
	v_exp_f32_e32 v58, v50
	v_sub_f32_e32 v50, v109, v45
	v_sub_f32_e32 v44, v44, v45
	v_sub_f32_e32 v121, v98, v45
	v_exp_f32_e32 v36, v32
	v_sub_f32_e32 v32, v100, v45
	v_exp_f32_e32 v37, v33
	v_sub_f32_e32 v33, v48, v45
	v_exp_f32_e32 v42, v41
	v_sub_f32_e32 v41, v53, v45
	v_exp_f32_e32 v60, v50
	v_sub_f32_e32 v50, v57, v45
	v_exp_f32_e32 v98, v44
	v_sub_f32_e32 v44, v114, v45
	v_exp_f32_e32 v32, v32
	v_exp_f32_e32 v33, v33
	v_exp_f32_e32 v39, v35
	v_sub_f32_e32 v35, v49, v45
	v_sub_f32_e32 v40, v51, v45
	v_exp_f32_e32 v48, v41
	v_sub_f32_e32 v41, v105, v45
	v_sub_f32_e32 v43, v54, v45
	v_exp_f32_e32 v62, v50
	v_sub_f32_e32 v50, v110, v45
	v_exp_f32_e32 v100, v44
	v_sub_f32_e32 v44, v115, v45
	v_exp_f32_e32 v35, v35
	v_exp_f32_e32 v40, v40
	v_exp_f32_e32 v41, v41
	v_exp_f32_e32 v47, v43
	v_sub_f32_e32 v43, v106, v45
	v_sub_f32_e32 v49, v55, v45
	v_exp_f32_e32 v57, v50
	v_sub_f32_e32 v50, v111, v45
	v_exp_f32_e32 v102, v44
	v_sub_f32_e32 v44, v116, v45
	v_exp_f32_e32 v43, v43
	v_exp_f32_e32 v49, v49
	v_exp_f32_e32 v59, v50
	v_sub_f32_e32 v50, v112, v45
	v_exp_f32_e32 v104, v44
	v_sub_f32_e32 v44, v117, v45
	v_exp_f32_e32 v61, v50
	v_sub_f32_e32 v50, v113, v45
	v_exp_f32_e32 v99, v44
	v_sub_f32_e32 v44, v118, v45
	v_exp_f32_e32 v63, v50
	v_exp_f32_e32 v101, v44
	v_sub_f32_e32 v44, v119, v45
	v_add_f32_e32 v50, v32, v36
	v_add_f32_e32 v51, v33, v37
	v_exp_f32_e32 v103, v44
	v_sub_f32_e32 v44, v120, v45
	v_add_f32_e32 v52, v34, v38
	v_add_f32_e32 v53, v35, v39
	v_add_f32_e32 v54, v46, v40
	v_add_f32_e32 v55, v47, v41
	v_exp_f32_e32 v105, v44
	v_add_f32_e32 v50, v54, v50
	v_add_f32_e32 v51, v55, v51
	v_add_f32_e32 v54, v48, v42
	v_add_f32_e32 v55, v49, v43
	v_exp_f32_e32 v44, v121
	v_add_f32_e32 v52, v54, v52
	v_add_f32_e32 v53, v55, v53
	v_add_f32_e32 v54, v58, v56
	v_add_f32_e32 v55, v59, v57
	v_mul_f32_e32 v14, v14, v44
	v_mul_f32_e32 v15, v15, v44
	v_add_f32_e32 v50, v54, v50
	v_add_f32_e32 v51, v55, v51
	v_add_f32_e32 v54, v62, v60
	v_add_f32_e32 v55, v63, v61
	v_mul_f32_e32 v12, v12, v44
	v_mul_f32_e32 v13, v13, v44
	v_add_f32_e32 v52, v54, v52
	v_add_f32_e32 v53, v55, v53
	v_add_f32_e32 v54, v100, v98
	v_add_f32_e32 v55, v101, v99
	v_mul_f32_e32 v10, v10, v44
	v_mul_f32_e32 v11, v11, v44
	v_add_f32_e32 v50, v54, v50
	v_add_f32_e32 v51, v55, v51
	v_add_f32_e32 v54, v104, v102
	v_add_f32_e32 v55, v105, v103
	v_mul_f32_e32 v8, v8, v44
	v_mul_f32_e32 v9, v9, v44
	v_add_f32_e32 v52, v54, v52
	v_add_f32_e32 v53, v55, v53
	v_cvt_pk_bf16_f32 v54, v40, v42
	v_add_f32_e32 v50, v50, v52
	v_add_f32_e32 v51, v51, v53
	v_cvt_pk_bf16_f32 v52, v36, v38
	v_cvt_pk_bf16_f32 v53, v37, v39
	v_cvt_pk_bf16_f32 v55, v41, v43
	v_cvt_pk_bf16_f32 v40, v56, v60
	v_cvt_pk_bf16_f32 v41, v57, v61
	v_cvt_pk_bf16_f32 v36, v32, v34
	v_cvt_pk_bf16_f32 v37, v33, v35
	v_cvt_pk_bf16_f32 v38, v46, v48
	v_cvt_pk_bf16_f32 v39, v47, v49
	v_cvt_pk_bf16_f32 v32, v58, v62
	v_cvt_pk_bf16_f32 v33, v59, v63
	ds_read_b128 v[46:49], v97 offset:18432
	ds_read_b128 v[56:59], v97 offset:23040
	v_mul_f32_e32 v6, v6, v44
	v_mul_f32_e32 v7, v7, v44
	v_mul_f32_e32 v4, v4, v44
	v_mul_f32_e32 v5, v5, v44
	v_mul_f32_e32 v2, v2, v44
	v_mul_f32_e32 v3, v3, v44
	v_mul_f32_e32 v0, v0, v44
	v_mul_f32_e32 v1, v1, v44
	v_mul_f32_e32 v30, v30, v44
	v_mul_f32_e32 v31, v31, v44
	v_mul_f32_e32 v28, v28, v44
	v_mul_f32_e32 v29, v29, v44
	v_mul_f32_e32 v26, v26, v44
	v_mul_f32_e32 v27, v27, v44
	v_mul_f32_e32 v24, v24, v44
	v_mul_f32_e32 v25, v25, v44
	v_mul_f32_e32 v22, v22, v44
	v_mul_f32_e32 v23, v23, v44
	v_mul_f32_e32 v20, v20, v44
	v_mul_f32_e32 v21, v21, v44
	v_mul_f32_e32 v18, v18, v44
	v_mul_f32_e32 v19, v19, v44
	v_mul_f32_e32 v16, v16, v44
	v_mul_f32_e32 v17, v17, v44
	s_waitcnt lgkmcnt(1)
	v_mfma_f32_32x32x16_bf16 v[0:15], v[46:49], v[52:55], v[0:15]
	v_cvt_pk_bf16_f32 v42, v98, v102
	v_cvt_pk_bf16_f32 v43, v99, v103
	v_cvt_pk_bf16_f32 v34, v100, v104
	v_cvt_pk_bf16_f32 v35, v101, v105
	v_add_f32_e32 v50, v50, v51
	v_fmac_f32_e32 v50, v94, v44
	v_mov_b32_e32 v94, v50
	s_waitcnt lgkmcnt(0)
	v_mfma_f32_32x32x16_bf16 v[16:31], v[56:59], v[52:55], v[16:31]
	ds_read_b128 v[46:49], v97 offset:18464
	ds_read_b128 v[52:55], v97 offset:23072
	v_mov_b32_e32 v98, v45
	s_waitcnt lgkmcnt(1)
	v_mfma_f32_32x32x16_bf16 v[0:15], v[46:49], v[40:43], v[0:15]
	s_waitcnt lgkmcnt(0)
	v_mfma_f32_32x32x16_bf16 v[16:31], v[52:55], v[40:43], v[16:31]
	ds_read_b128 v[40:43], v97 offset:18496
	ds_read_b128 v[46:49], v97 offset:23104
	s_waitcnt lgkmcnt(1)
	v_mfma_f32_32x32x16_bf16 v[0:15], v[40:43], v[36:39], v[0:15]
	s_waitcnt lgkmcnt(0)
	v_mfma_f32_32x32x16_bf16 v[16:31], v[46:49], v[36:39], v[16:31]
	ds_read_b128 v[36:39], v97 offset:18528
	ds_read_b128 v[40:43], v97 offset:23136
	s_waitcnt lgkmcnt(1)
	v_mfma_f32_32x32x16_bf16 v[0:15], v[36:39], v[32:35], v[0:15]
	s_waitcnt lgkmcnt(0)
	v_mfma_f32_32x32x16_bf16 v[16:31], v[40:43], v[32:35], v[16:31]
	s_branch .LBB0_264
